# write-through (sc1) 16-byte PQ stores in the scan pass-1 item epilogue (published right before a grid barrier)
# speedup vs baseline: 1.0100x; 1.0076x over previous
.LBB0_317:
	s_waitcnt vmcnt(0)
	v_mov_b64_e32 v[202:203], 0x83f
	v_mov_b32_e32 v240, 1
	v_mov_b32_e32 v241, 0x3727c5ac
	v_mov_b32_e32 v242, 0x260
	v_mov_b32_e32 v243, 0x2200
	v_mov_b32_e32 v244, 0x58
	v_mov_b32_e32 v245, 0x48
	v_mbcnt_lo_u32_b32 v0, -1, 0
	v_mbcnt_hi_u32_b32 v0, -1, v0
	s_ashr_i32 s7, s6, 31
	v_and_b32_e32 v1, 15, v0
	v_lshlrev_b32_e32 v2, 4, v0
	s_waitcnt vmcnt(3)
	v_and_b32_e32 v132, 0x300, v2
	v_lshlrev_b32_e32 v133, 2, v1
	v_add3_u32 v132, s33, v132, v133
	v_lshlrev_b32_e32 v1, 6, v1
	v_and_b32_e32 v0, 48, v0
	v_add3_u32 v133, s33, v1, v0
	v_add_u32_e32 v134, 0x4800, v132
	v_add_u32_e32 v132, 0x4c00, v132
	ds_write2_b32 v134, v24, v25 offset0:128 offset1:144
	ds_write2_b32 v134, v26, v27 offset0:160 offset1:176
	ds_write2_b32 v132, v12, v13 offset0:128 offset1:144
	ds_write2_b32 v132, v14, v15 offset0:160 offset1:176
	ds_read_b128 v[12:15], v133 offset:18944
	ds_read_b128 v[24:27], v133 offset:19968
	s_lshl_b64 s[6:7], s[6:7], 15
	s_add_u32 s6, s34, s6
	s_addc_u32 s7, s35, s7
	s_waitcnt lgkmcnt(1)
	v_cvt_pk_bf16_f32 v12, v12, v13
	v_cvt_pk_bf16_f32 v13, v14, v15
	s_waitcnt lgkmcnt(0)
	v_cvt_pk_bf16_f32 v14, v24, v25
	v_cvt_pk_bf16_f32 v15, v26, v27
	v_and_b32_e32 v2, 0x3f0, v2
	global_store_dwordx4 v2, v[12:15], s[6:7]
	ds_write2_b32 v134, v96, v97 offset0:128 offset1:144
	ds_write2_b32 v134, v98, v99 offset0:160 offset1:176
	ds_write2_b32 v132, v108, v109 offset0:128 offset1:144
	ds_write2_b32 v132, v110, v111 offset0:160 offset1:176
	ds_read_b128 v[12:15], v133 offset:18944
	ds_read_b128 v[24:27], v133 offset:19968
	v_lshl_add_u64 v[0:1], s[6:7], 0, v[2:3]
	s_add_i32 s36, s36, s56
	s_cmp_ge_i32 s36, s60
	s_waitcnt lgkmcnt(1)
	v_cvt_pk_bf16_f32 v12, v12, v13
	v_cvt_pk_bf16_f32 v13, v14, v15
	s_waitcnt lgkmcnt(0)
	v_cvt_pk_bf16_f32 v14, v24, v25
	v_cvt_pk_bf16_f32 v15, v26, v27
	global_store_dwordx4 v2, v[12:15], s[6:7] offset:2048
	ds_write2_b32 v134, v68, v69 offset0:128 offset1:144
	ds_write2_b32 v134, v70, v71 offset0:160 offset1:176
	ds_write2_b32 v132, v72, v73 offset0:128 offset1:144
	ds_write2_b32 v132, v74, v75 offset0:160 offset1:176
	ds_read_b128 v[12:15], v133 offset:18944
	ds_read_b128 v[24:27], v133 offset:19968
	v_add_co_u32_e32 v68, vcc, s19, v0
	s_movk_i32 s6, 0x5000
	s_waitcnt lgkmcnt(1)
	v_cvt_pk_bf16_f32 v12, v12, v13
	v_cvt_pk_bf16_f32 v13, v14, v15
	s_waitcnt lgkmcnt(0)
	v_cvt_pk_bf16_f32 v14, v24, v25
	v_cvt_pk_bf16_f32 v15, v26, v27
	v_addc_co_u32_e32 v69, vcc, 0, v1, vcc
	global_store_dwordx4 v[68:69], v[12:15], off offset:-4096
	ds_write2_b32 v134, v36, v37 offset0:128 offset1:144
	ds_write2_b32 v134, v38, v39 offset0:160 offset1:176
	ds_write2_b32 v132, v32, v33 offset0:128 offset1:144
	ds_write2_b32 v132, v34, v35 offset0:160 offset1:176
	ds_read_b128 v[12:15], v133 offset:18944
	ds_read_b128 v[24:27], v133 offset:19968
	v_add_co_u32_e32 v32, vcc, s31, v0
	s_waitcnt lgkmcnt(1)
	v_cvt_pk_bf16_f32 v12, v12, v13
	v_addc_co_u32_e32 v33, vcc, 0, v1, vcc
	v_cvt_pk_bf16_f32 v13, v14, v15
	s_waitcnt lgkmcnt(0)
	v_cvt_pk_bf16_f32 v14, v24, v25
	v_cvt_pk_bf16_f32 v15, v26, v27
	global_store_dwordx4 v[32:33], v[12:15], off offset:2048
	ds_write2_b32 v134, v116, v117 offset0:128 offset1:144
	ds_write2_b32 v134, v118, v119 offset0:160 offset1:176
	ds_write2_b32 v132, v124, v125 offset0:128 offset1:144
	ds_write2_b32 v132, v126, v127 offset0:160 offset1:176
	ds_read_b128 v[12:15], v133 offset:18944
	ds_read_b128 v[24:27], v133 offset:19968
	s_waitcnt lgkmcnt(1)
	v_cvt_pk_bf16_f32 v12, v12, v13
	v_cvt_pk_bf16_f32 v13, v14, v15
	s_waitcnt lgkmcnt(0)
	v_cvt_pk_bf16_f32 v14, v24, v25
	v_cvt_pk_bf16_f32 v15, v26, v27
	global_store_dwordx4 v[68:69], v[12:15], off
	ds_write2_b32 v134, v16, v17 offset0:128 offset1:144
	ds_write2_b32 v134, v18, v19 offset0:160 offset1:176
	ds_write2_b32 v132, v20, v21 offset0:128 offset1:144
	ds_write2_b32 v132, v22, v23 offset0:160 offset1:176
	ds_read_b128 v[12:15], v133 offset:18944
	ds_read_b128 v[16:19], v133 offset:19968
	s_waitcnt lgkmcnt(1)
	v_cvt_pk_bf16_f32 v12, v12, v13
	v_cvt_pk_bf16_f32 v13, v14, v15
	s_waitcnt lgkmcnt(0)
	v_cvt_pk_bf16_f32 v14, v16, v17
	v_cvt_pk_bf16_f32 v15, v18, v19
	global_store_dwordx4 v[68:69], v[12:15], off offset:2048
	ds_write2_b32 v134, v56, v57 offset0:128 offset1:144
	ds_write2_b32 v134, v58, v59 offset0:160 offset1:176
	ds_write2_b32 v132, v44, v45 offset0:128 offset1:144
	ds_write2_b32 v132, v46, v47 offset0:160 offset1:176
	ds_read_b128 v[12:15], v133 offset:18944
	ds_read_b128 v[16:19], v133 offset:19968
	s_waitcnt lgkmcnt(1)
	v_cvt_pk_bf16_f32 v12, v12, v13
	v_cvt_pk_bf16_f32 v13, v14, v15
	s_waitcnt lgkmcnt(0)
	v_cvt_pk_bf16_f32 v14, v16, v17
	v_add_co_u32_e32 v16, vcc, s2, v0
	v_cvt_pk_bf16_f32 v15, v18, v19
	s_nop 0
	v_addc_co_u32_e32 v17, vcc, 0, v1, vcc
	global_store_dwordx4 v[16:17], v[12:15], off offset:-4096
	ds_write2_b32 v134, v28, v29 offset0:128 offset1:144
	ds_write2_b32 v134, v30, v31 offset0:160 offset1:176
	ds_write2_b32 v132, v4, v5 offset0:128 offset1:144
	ds_write2_b32 v132, v6, v7 offset0:160 offset1:176
	ds_read_b128 v[4:7], v133 offset:18944
	ds_read_b128 v[12:15], v133 offset:19968
	v_add_co_u32_e32 v18, vcc, s64, v0
	s_waitcnt lgkmcnt(1)
	v_cvt_pk_bf16_f32 v4, v4, v5
	v_addc_co_u32_e32 v19, vcc, 0, v1, vcc
	v_cvt_pk_bf16_f32 v5, v6, v7
	s_waitcnt lgkmcnt(0)
	v_cvt_pk_bf16_f32 v6, v12, v13
	v_cvt_pk_bf16_f32 v7, v14, v15
	global_store_dwordx4 v[18:19], v[4:7], off offset:2048
	s_nop 1
	v_lshl_add_u64 v[4:5], v[0:1], 0, s[26:27]
	global_store_dwordx4 v[16:17], v[104:107], off
	global_store_dwordx4 v[4:5], v[88:91], off offset:1024
	global_store_dwordx4 v[4:5], v[40:43], off offset:2048
	global_store_dwordx4 v[4:5], v[8:11], off offset:3072
	v_add_co_u32_e32 v4, vcc, s6, v0
	s_nop 1
	v_addc_co_u32_e32 v5, vcc, 0, v1, vcc
	v_add_co_u32_e32 v6, vcc, s3, v0
	s_nop 1
	v_addc_co_u32_e32 v7, vcc, 0, v1, vcc
	v_add_co_u32_e32 v0, vcc, 0x7000, v0
	global_store_dwordx4 v[6:7], v[92:95], off offset:-4096 sc1
	global_store_dwordx4 v[4:5], v[80:83], off offset:1024 sc1
	global_store_dwordx4 v[4:5], v[64:67], off offset:2048 sc1
	global_store_dwordx4 v[4:5], v[52:55], off offset:3072 sc1
	global_store_dwordx4 v[6:7], v[128:131], off sc1
	global_store_dwordx4 v[6:7], v[84:87], off offset:1024 sc1
	global_store_dwordx4 v[6:7], v[100:103], off offset:2048 sc1
	global_store_dwordx4 v[6:7], v[60:63], off offset:3072 sc1
	v_addc_co_u32_e32 v1, vcc, 0, v1, vcc
	global_store_dwordx4 v[0:1], v[120:123], off sc1
	global_store_dwordx4 v[0:1], v[112:115], off offset:1024 sc1
	global_store_dwordx4 v[0:1], v[76:79], off offset:2048 sc1
	global_store_dwordx4 v[0:1], v[48:51], off offset:3072 sc1
	s_cbranch_scc1 .LBB0_336
